# code placement: D latent tile loop (and all code after it) shifted by 4 bytes so the hand-scheduled loop head sits on an 8-byte boundary
# speedup vs baseline: 1.0078x; 1.0040x over previous
; #define LAS __attribute__((address_space(3)))
; #define GAS __attribute__((address_space(1)))
; #define ISSUE(t, KR, VR) do { const GAS bf16_t* tb_ = (const GAS bf16_t*)Z + (size_t)TILE_ROW(t) * ZW; \
;         KR[0] = *(const GAS u32x4*)(tb_ + koff); KR[1] = *(const GAS u32x4*)(tb_ + koff + 64); \
;         VR[0] = *(const GAS u32x4*)(tb_ + voff); VR[1] = *(const GAS u32x4*)(tb_ + voff + ZW); } while (0)
; DI void attn_unit_d32(const Ctx& C, const bf16_t* __restrict__ Z, bf16_t* __restrict__ Y, int b, int qsel, int hsel, bool ctxq, float lam, float post_scale, const float* subln, const float mref) {
;     ...
;     const int tid = C.tid, lane = C.lane, w = C.wave, l31 = lane & 31, hh = lane >> 5, sm = w >> 2, qg = w & 3;
;     const int qrow = (ctxq ? NLAT + 256 * b : b * SEQ) + 128 * qsel + 32 * qg + l31;
;     const int qcol = Z_DQ + 128 * hsel + 64 * sm, kcol = Z_DK + 128 * hsel, vcol = Z_DV + 128 * hsel, ycol = 1536 + 128 * hsel;
;     const int nt = ctxq ? 4 : 36;
;     LAS bf16_t* lds16 = (LAS bf16_t*)C.lds;
;     bf16x8 qf[4];
; #pragma unroll
;     for (int ks = 0; ks < 4; ++ks) qf[ks] = *(const GAS bf16x8*)(Z + (size_t)qrow * ZW + qcol + 16 * ks + 8 * hh);
;     const float negm = -mref;
;     f32x16 o[4]; float lsum = 0.f;
; #pragma unroll
;     for (int d = 0; d < 4; ++d)
; #pragma unroll
;         for (int r = 0; r < 16; ++r) o[d][r] = 0.f;
;     u32x4 kA[2], vA[2], kB[2], vB[2];
;     const int krow = tid >> 3, kch = tid & 7, vp2 = 2 * (lane & 31), vhs = lane >> 5;
;     ...
;     const unsigned koff = (unsigned)(krow * ZW + kcol + 8 * kch), voff = (unsigned)(vp2 * ZW + vcol + 8 * (2 * w + vhs));
;     ...
;     ISSUE(0, kA, vA); ISSUE(1, kB, vB);
;     __syncthreads();
;     WRITE(0, kA, vA); ISSUE(2, kA, vA);
;     __syncthreads();
.LBB0_397:
	s_ashr_i32 s21, s20, 6
	s_lshl_b32 s0, s21, 8
	s_mul_i32 s1, s21, 0x220000
	s_lshl_b32 s22, s21, 11
	s_lshl_b32 s21, s20, 5
	s_and_b32 s21, s21, 0x780
	v_or_b32_e32 v0, s21, v187
	s_lshl_b32 s21, s20, 7
	s_and_b32 s21, s21, 0x180
	v_or_b32_e32 v172, s22, v0
	s_add_i32 s24, s19, s21
	v_mov_b64_e32 v[20:21], s[8:9]
	v_mad_i64_i32 v[20:21], s[28:29], v172, s53, v[20:21]
	s_ashr_i32 s25, s24, 31
	s_add_i32 s36, s0, 0x2000
	v_lshl_add_u64 v[20:21], s[24:25], 1, v[20:21]
	s_add_i32 s24, s1, 0x4400000
	v_add_u32_e32 v0, s21, v179
	s_mul_hi_i32 s25, s36, 0x2200
	s_add_u32 s24, s8, s24
	v_lshl_add_u64 v[20:21], v[2:3], 1, v[20:21]
	v_add_u32_e32 v174, s21, v180
	s_addc_u32 s25, s9, s25
	v_lshlrev_b64 v[36:37], 1, v[0:1]
	v_mov_b32_e32 v175, v1
	global_load_dwordx4 v[116:119], v[20:21], off
	global_load_dwordx4 v[120:123], v[20:21], off offset:32
	global_load_dwordx4 v[124:127], v[20:21], off offset:64
	global_load_dwordx4 v[128:131], v[20:21], off offset:96
	v_lshl_add_u64 v[20:21], s[24:25], 0, v[36:37]
	v_lshlrev_b64 v[38:39], 1, v[174:175]
	global_load_dwordx4 v[40:43], v[20:21], off
	global_load_dwordx4 v[44:47], v[20:21], off offset:128
	v_lshl_add_u64 v[20:21], s[24:25], 0, v[38:39]
	global_load_dwordx4 v[48:51], v[20:21], off
	v_add_co_u32_e32 v20, vcc, s41, v20
	s_add_i32 s24, s0, 0x2040
	s_nop 0
	v_addc_co_u32_e32 v21, vcc, 0, v21, vcc
	global_load_dwordx4 v[52:55], v[20:21], off offset:512
	s_add_i32 s25, s1, 0x4488000
	s_mul_hi_i32 s28, s24, 0x2200
	s_add_u32 s24, s8, s25
	s_addc_u32 s25, s9, s28
	v_lshl_add_u64 v[20:21], s[24:25], 0, v[36:37]
	v_lshl_add_u64 v[24:25], s[24:25], 0, v[38:39]
	global_load_dwordx4 v[28:31], v[20:21], off
	global_load_dwordx4 v[32:35], v[20:21], off offset:128
	v_add_u32_e32 v191, 0x4400, v182
	global_load_dwordx4 v[20:23], v[24:25], off
	v_add_co_u32_e32 v24, vcc, s41, v24
	s_add_i32 s24, s0, 0x2080
	s_nop 0
	v_addc_co_u32_e32 v25, vcc, 0, v25, vcc
	global_load_dwordx4 v[24:27], v[24:25], off offset:512
	s_barrier
	s_add_i32 s1, s1, 0x4510000
	s_mul_hi_i32 s25, s24, 0x2200
	s_add_u32 s24, s8, s1
	s_addc_u32 s25, s9, s25
	v_add_u32_e32 v192, 0xd400, v182
	s_addk_i32 s0, 0x20c0
	s_mul_hi_i32 s1, s0, 0x2200
	s_mulk_i32 s0, 0x2200
	s_add_u32 s0, s8, s0
	s_addc_u32 s1, s9, s1
	v_add_u32_e32 v219, 0x7800, v189
	v_ashrrev_i32_e32 v173, 31, v172
	s_mov_b32 s23, 1
	s_waitcnt vmcnt(7)
	ds_write_b128 v181, v[40:43]
	s_waitcnt vmcnt(6)
	ds_write_b128 v181, v[44:47] offset:128
	s_waitcnt vmcnt(5)
	v_and_b32_e32 v40, 0xffff, v48
	v_lshrrev_b32_e32 v41, 16, v48
	s_waitcnt vmcnt(4)
	v_lshl_or_b32 v40, v52, 16, v40
	v_and_or_b32 v41, v52, s39, v41
	ds_write2_b32 v191, v40, v41 offset1:36
	v_and_b32_e32 v40, 0xffff, v49
	v_lshrrev_b32_e32 v41, 16, v49
	v_lshl_or_b32 v40, v53, 16, v40
	v_and_or_b32 v41, v53, s39, v41
	ds_write2_b32 v191, v40, v41 offset0:72 offset1:108
	v_and_b32_e32 v40, 0xffff, v50
	v_lshrrev_b32_e32 v41, 16, v50
	v_lshl_or_b32 v40, v54, 16, v40
	v_and_or_b32 v41, v54, s39, v41
	ds_write2_b32 v191, v40, v41 offset0:144 offset1:180
	v_and_b32_e32 v40, 0xffff, v51
	v_lshrrev_b32_e32 v41, 16, v51
	v_lshl_or_b32 v40, v55, 16, v40
	v_and_or_b32 v41, v55, s39, v41
	ds_write2_b32 v191, v40, v41 offset0:216 offset1:252
	v_lshl_add_u64 v[40:41], s[24:25], 0, v[36:37]
	global_load_dwordx4 v[136:139], v[40:41], off
	global_load_dwordx4 v[132:135], v[40:41], off offset:128
	v_lshl_add_u64 v[40:41], s[24:25], 0, v[38:39]
	global_load_dwordx4 v[140:143], v[40:41], off
	v_add_co_u32_e32 v40, vcc, s41, v40
	s_nop 1
	v_addc_co_u32_e32 v41, vcc, 0, v41, vcc
	global_load_dwordx4 v[144:147], v[40:41], off offset:512
	s_waitcnt lgkmcnt(0)
	s_barrier
; #define LAS __attribute__((address_space(3)))
; DI unsigned pk2(float lo, float hi) { f32x2 v = {lo, hi}; bf16x2_t b = __builtin_convertvector(v, bf16x2_t); return __builtin_bit_cast(unsigned, b); }
; DI void attn_unit_d32(const Ctx& C, const bf16_t* __restrict__ Z, bf16_t* __restrict__ Y, int b, int qsel, int hsel, bool ctxq, float lam, float post_scale, const float* subln, const float mref) {
;     ...
;     for (int t = 0; t < nt; ++t) {
;         if (t + 1 < nt) {
;             if ((t + 1) & 1) { WRITE(1, kB, vB); if (t + 3 < nt) ISSUE(t + 3, kB, vB); }
;             else { WRITE(0, kA, vA); if (t + 3 < nt) ISSUE(t + 3, kA, vA); }
;         }
;         const LAS bf16_t* Ks = lds16 + ((t & 1) * AT_BUF) / 2 + 64 * sm; const LAS bf16_t* Vt = lds16 + ((t & 1) * AT_BUF + AT_VT) / 2;
;         f32x16 st[2];
; #pragma unroll
;         for (int kb = 0; kb < 2; ++kb) {
; #pragma unroll
;             for (int r = 0; r < 16; ++r) st[kb][r] = negm;
; #pragma unroll
;             for (int ks = 0; ks < 4; ++ks) { const bf16x8 a = *(const LAS bf16x8*)(Ks + (32 * kb + l31) * KST + 16 * ks + 8 * hh);
;                 st[kb] = __builtin_amdgcn_mfma_f32_32x32x16_bf16(a, qf[ks], st[kb], 0, 0, 0); } }
;         bf16x8 pf[2][2]; float ps = 0.f;
; #pragma unroll
;         for (int kb = 0; kb < 2; ++kb) {
; #pragma unroll
;             for (int r = 0; r < 16; ++r) { const float p = fast_exp2(st[kb][r]); st[kb][r] = p; ps += p; }
; #pragma unroll
;             for (int s = 0; s < 2; ++s) { u32x4 pw; pw.x = pk2(st[kb][8 * s], st[kb][8 * s + 1]); pw.y = pk2(st[kb][8 * s + 2], st[kb][8 * s + 3]); pw.z = pk2(st[kb][8 * s + 4], st[kb][8 * s + 5]); pw.w = pk2(st[kb][8 * s + 6], st[kb][8 * s + 7]);
;                 pf[kb][s] = __builtin_bit_cast(bf16x8, pw); } }
;         lsum += ps;
; #pragma unroll
;         for (int d = 0; d < 4; ++d)
; #pragma unroll
;             for (int kb = 0; kb < 2; ++kb)
; #pragma unroll
;                 for (int s = 0; s < 2; ++s) { const LAS bf16_t* vp = Vt + (32 * d + l31) * VST + 32 * kb + 16 * s + 4 * hh;
;                     const u32x2 lo = *(const LAS u32x2*)vp, hi = *(const LAS u32x2*)(vp + 8);
;                     u32x4 av; av.x = lo.x; av.y = lo.y; av.z = hi.x; av.w = hi.y;
;                     o[d] = __builtin_amdgcn_mfma_f32_32x32x16_bf16(__builtin_bit_cast(bf16x8, av), pf[kb][s], o[d], 0, 0, 0); }
;         __syncthreads();
	s_waitcnt vmcnt(7)
	ds_write_b128 v181, v[28:31] offset:36864
	s_waitcnt vmcnt(6)
	ds_write_b128 v181, v[32:35] offset:36992
	s_waitcnt vmcnt(5)
	v_and_b32_e32 v28, 0xffff, v20
	v_lshrrev_b32_e32 v20, 16, v20
	s_waitcnt vmcnt(4)
	v_lshl_or_b32 v28, v24, 16, v28
	v_and_or_b32 v20, v24, s39, v20
	ds_write2_b32 v192, v28, v20 offset1:36
	v_and_b32_e32 v20, 0xffff, v21
	v_lshrrev_b32_e32 v21, 16, v21
	v_lshl_or_b32 v20, v25, 16, v20
	v_and_or_b32 v21, v25, s39, v21
	ds_write2_b32 v192, v20, v21 offset0:72 offset1:108
	v_and_b32_e32 v20, 0xffff, v22
	v_lshrrev_b32_e32 v21, 16, v22
	v_lshl_or_b32 v20, v26, 16, v20
	v_and_or_b32 v21, v26, s39, v21
	ds_write2_b32 v192, v20, v21 offset0:144 offset1:180
	v_and_b32_e32 v20, 0xffff, v23
	v_lshrrev_b32_e32 v21, 16, v23
	v_lshl_or_b32 v20, v27, 16, v20
	v_and_or_b32 v21, v27, s39, v21
	ds_write2_b32 v192, v20, v21 offset0:216 offset1:252
	v_lshl_add_u64 v[20:21], s[0:1], 0, v[36:37]
	global_load_dwordx4 v[148:151], v[20:21], off
	global_load_dwordx4 v[152:155], v[20:21], off offset:128
	v_lshl_add_u64 v[20:21], s[0:1], 0, v[38:39]
	global_load_dwordx4 v[156:159], v[20:21], off
	v_add_co_u32_e32 v20, vcc, s41, v20
	s_nop 1
	v_addc_co_u32_e32 v21, vcc, 0, v21, vcc
	global_load_dwordx4 v[160:163], v[20:21], off offset:512
	ds_read_b128 v[20:23], v188
	ds_read_b128 v[24:27], v188 offset:32
	s_waitcnt lgkmcnt(1)
	v_mfma_f32_32x32x16_bf16 v[36:51], v[20:23], v[116:119], v[4:19]
	ds_read_b128 v[20:23], v188 offset:64
	ds_read_b128 v[52:55], v188 offset:8704
	s_waitcnt lgkmcnt(2)
	v_mfma_f32_32x32x16_bf16 v[36:51], v[24:27], v[120:123], v[36:51]
	s_waitcnt lgkmcnt(1)
	v_mfma_f32_32x32x16_bf16 v[36:51], v[20:23], v[124:127], v[36:51]
	ds_read_b128 v[20:23], v188 offset:96
	s_waitcnt lgkmcnt(0)
	v_mfma_f32_32x32x16_bf16 v[36:51], v[20:23], v[128:131], v[36:51]
	v_mfma_f32_32x32x16_bf16 v[20:35], v[52:55], v[116:119], v[4:19]
	ds_read_b128 v[52:55], v188 offset:8736
	s_nop 9
	v_exp_f32_e32 v100, v36
	v_exp_f32_e32 v101, v37
	v_exp_f32_e32 v102, v38
	v_exp_f32_e32 v103, v39
	v_exp_f32_e32 v104, v40
	v_exp_f32_e32 v105, v41
	s_waitcnt lgkmcnt(0)
	v_mfma_f32_32x32x16_bf16 v[20:35], v[52:55], v[120:123], v[20:35]
	ds_read_b128 v[52:55], v188 offset:8768
	v_exp_f32_e32 v106, v42
	v_exp_f32_e32 v107, v43
	v_cvt_pk_bf16_f32 v92, v100, v101
	v_cvt_pk_bf16_f32 v93, v102, v103
	v_cvt_pk_bf16_f32 v94, v104, v105
	v_cvt_pk_bf16_f32 v95, v106, v107
	s_waitcnt lgkmcnt(0)
	v_mfma_f32_32x32x16_bf16 v[20:35], v[52:55], v[124:127], v[20:35]
	ds_read_b128 v[52:55], v188 offset:8800
	v_exp_f32_e32 v108, v44
	v_exp_f32_e32 v109, v45
	v_exp_f32_e32 v110, v46
	v_exp_f32_e32 v111, v47
	v_exp_f32_e32 v112, v48
	v_exp_f32_e32 v113, v49
	s_waitcnt lgkmcnt(0)
	v_mfma_f32_32x32x16_bf16 v[20:35], v[52:55], v[128:131], v[20:35]
	v_exp_f32_e32 v114, v50
	v_exp_f32_e32 v115, v51
	v_cvt_pk_bf16_f32 v88, v108, v109
	v_cvt_pk_bf16_f32 v89, v110, v111
	v_cvt_pk_bf16_f32 v90, v112, v113
	v_cvt_pk_bf16_f32 v91, v114, v115
	s_nop 5
	v_exp_f32_e32 v211, v28
	v_add_u32_e32 v28, 0x4000, v189
	v_exp_f32_e32 v193, v20
	v_exp_f32_e32 v194, v21
	v_exp_f32_e32 v195, v22
	v_exp_f32_e32 v203, v23
	v_exp_f32_e32 v205, v24
	v_exp_f32_e32 v207, v25
	v_exp_f32_e32 v209, v26
	v_exp_f32_e32 v210, v27
	ds_read_b128 v[20:23], v28 offset:1024
	ds_read_b128 v[24:27], v28 offset:1056
	s_waitcnt lgkmcnt(1)
	v_mfma_f32_32x32x16_bf16 v[68:83], v[20:23], v[92:95], 0
	ds_read_b128 v[20:23], v28 offset:1088
	v_cvt_pk_bf16_f32 v96, v193, v194
	v_cvt_pk_bf16_f32 v97, v195, v203
	v_cvt_pk_bf16_f32 v98, v205, v207
	v_cvt_pk_bf16_f32 v99, v209, v210
	v_exp_f32_e32 v212, v29
	v_exp_f32_e32 v213, v30
	s_waitcnt lgkmcnt(1)
	v_mfma_f32_32x32x16_bf16 v[68:83], v[24:27], v[88:91], v[68:83]
	v_exp_f32_e32 v214, v31
	v_exp_f32_e32 v215, v32
	v_exp_f32_e32 v216, v33
	v_exp_f32_e32 v217, v34
	v_exp_f32_e32 v218, v35
	v_cvt_pk_bf16_f32 v84, v211, v212
	v_cvt_pk_bf16_f32 v85, v213, v214
	s_waitcnt lgkmcnt(0)
	v_mfma_f32_32x32x16_bf16 v[68:83], v[20:23], v[96:99], v[68:83]
	ds_read_b128 v[20:23], v28 offset:1120
	v_cvt_pk_bf16_f32 v86, v215, v216
	v_cvt_pk_bf16_f32 v87, v217, v218
	v_add_u32_e32 v24, 0x5000, v189
	s_waitcnt lgkmcnt(0)
	v_mfma_f32_32x32x16_bf16 v[68:83], v[20:23], v[84:87], v[68:83]
	ds_read_b128 v[20:23], v24 offset:1536
	s_waitcnt lgkmcnt(0)
	v_mfma_f32_32x32x16_bf16 v[52:67], v[20:23], v[92:95], 0
	ds_read_b128 v[20:23], v24 offset:1568
	s_waitcnt lgkmcnt(0)
	v_mfma_f32_32x32x16_bf16 v[52:67], v[20:23], v[88:91], v[52:67]
	ds_read_b128 v[20:23], v24 offset:1600
	s_waitcnt lgkmcnt(0)
	v_mfma_f32_32x32x16_bf16 v[52:67], v[20:23], v[96:99], v[52:67]
	ds_read_b128 v[20:23], v24 offset:1632
	v_add_u32_e32 v24, 0x6800, v189
	s_waitcnt lgkmcnt(0)
	v_mfma_f32_32x32x16_bf16 v[52:67], v[20:23], v[84:87], v[52:67]
	ds_read_b128 v[20:23], v24
	s_waitcnt lgkmcnt(0)
	v_mfma_f32_32x32x16_bf16 v[36:51], v[20:23], v[92:95], 0
	ds_read_b128 v[20:23], v24 offset:32
	s_waitcnt lgkmcnt(0)
	v_mfma_f32_32x32x16_bf16 v[36:51], v[20:23], v[88:91], v[36:51]
	ds_read_b128 v[20:23], v24 offset:64
	s_waitcnt lgkmcnt(0)
	v_mfma_f32_32x32x16_bf16 v[36:51], v[20:23], v[96:99], v[36:51]
	ds_read_b128 v[20:23], v24 offset:96
	s_waitcnt lgkmcnt(0)
	v_mfma_f32_32x32x16_bf16 v[36:51], v[20:23], v[84:87], v[36:51]
	ds_read_b128 v[20:23], v219 offset:512
	s_waitcnt lgkmcnt(0)
	v_mfma_f32_32x32x16_bf16 v[20:35], v[20:23], v[92:95], 0
	ds_read_b128 v[92:95], v219 offset:544
	s_waitcnt lgkmcnt(0)
	v_mfma_f32_32x32x16_bf16 v[20:35], v[92:95], v[88:91], v[20:35]
	ds_read_b128 v[88:91], v219 offset:576
	s_waitcnt lgkmcnt(0)
	v_mfma_f32_32x32x16_bf16 v[20:35], v[88:91], v[96:99], v[20:35]
	ds_read_b128 v[88:91], v219 offset:608
	s_waitcnt lgkmcnt(0)
	s_barrier
	v_mfma_f32_32x32x16_bf16 v[20:35], v[88:91], v[84:87], v[20:35]
	v_add_f32_e32 v84, 0, v100
	v_add_f32_e32 v84, v101, v84
	v_add_f32_e32 v84, v102, v84
	v_add_f32_e32 v84, v103, v84
	v_add_f32_e32 v84, v104, v84
	v_add_f32_e32 v84, v105, v84
	v_add_f32_e32 v84, v106, v84
	v_add_f32_e32 v84, v107, v84
	v_add_f32_e32 v84, v108, v84
	v_add_f32_e32 v84, v109, v84
	v_add_f32_e32 v84, v110, v84
	v_add_f32_e32 v84, v111, v84
	v_add_f32_e32 v84, v112, v84
	v_add_f32_e32 v84, v113, v84
	v_add_f32_e32 v84, v114, v84
	v_add_f32_e32 v84, v115, v84
	v_add_f32_e32 v84, v193, v84
	v_add_f32_e32 v84, v194, v84
	v_add_f32_e32 v84, v195, v84
	v_add_f32_e32 v84, v203, v84
	v_add_f32_e32 v84, v205, v84
	v_add_f32_e32 v84, v207, v84
	v_add_f32_e32 v84, v209, v84
	v_add_f32_e32 v84, v210, v84
	v_add_f32_e32 v84, v211, v84
	v_add_f32_e32 v84, v212, v84
	v_add_f32_e32 v84, v213, v84
	v_add_f32_e32 v84, v214, v84
	v_add_f32_e32 v84, v215, v84
	v_add_f32_e32 v84, v216, v84
	v_add_f32_e32 v84, v217, v84
	v_add_f32_e32 v84, v218, v84
	v_add_f32_e32 v193, 0, v84
	s_cmp_gt_u32 s23, 34
	s_cbranch_scc1 .LBB0_407
	s_branch .LBB0_399
	s_nop 0
